# group-barrier fast path: fire-and-forget arrive atomic + per-workgroup generation in LDS as poll target (no returned-value round trip); on top of v65
# baseline (speedup 1.0000x reference)
; __device__ __forceinline__ unsigned xb_ld(unsigned* p)              { return __hip_atomic_load(p, __ATOMIC_RELAXED, __HIP_MEMORY_SCOPE_AGENT); }
; __device__ __forceinline__ unsigned xb_add(unsigned* p, unsigned v) { return __hip_atomic_fetch_add(p, v, __ATOMIC_RELAXED, __HIP_MEMORY_SCOPE_AGENT); }
; #define XB_SPIN(cond, bar) do { unsigned _sp = 0; while (cond) { __builtin_amdgcn_s_sleep(1); \
;     if ((++_sp & 255u) == 0u) { if (xb_ld(&(bar)[XB_TMO])) break; if (_sp > XB_SPIN_CAP) { atomicAdd(&(bar)[XB_TMO], 1u); break; } } } } while (0)
; __device__ __forceinline__ void xcd_barrier(const XcdBarrier& b) {
;     asm volatile("s_waitcnt vmcnt(0)" ::: "memory");
;     __syncthreads();
;     if (threadIdx.x == 0) {
;         unsigned* bar = b.bar;
;         __builtin_amdgcn_s_waitcnt(0);
;         unsigned nloc = b.st[0], nx = b.st[1];
;         if (nloc == 0u) { xcd_barrier_complete(bar, b.x, nloc, nx); b.st[0] = nloc; b.st[1] = nx; }
;         const unsigned old = xb_add(&bar[XB_XSUB(b.x)], 1u);
;         const unsigned gen = old / nloc;
;         if (old + 1u == (gen + 1u) * nloc) {
;             __builtin_amdgcn_fence(__ATOMIC_RELEASE, "agent");
;             asm volatile("s_waitcnt vmcnt(0)" ::: "memory");
;             const unsigned og = xb_add(&bar[XB_TOP], 1u);
;             const unsigned tg = og / nx;
;             if (og + 1u == (tg + 1u) * nx) xb_add(&bar[XB_TOPGEN], 1u);
;             else XB_SPIN(xb_ld(&bar[XB_TOPGEN]) == tg, bar);
;             __builtin_amdgcn_fence(__ATOMIC_ACQUIRE, "agent");
;             xb_add(&bar[XB_XGEN(b.x)], 1u);
;             asm volatile("s_waitcnt vmcnt(0)" ::: "memory");
;         } else {
;             XB_SPIN(xb_ld(&bar[XB_XGEN(b.x)]) == gen, bar);
;             __builtin_amdgcn_fence(__ATOMIC_ACQUIRE, "agent");
;             asm volatile("s_waitcnt vmcnt(0)" ::: "memory");
;         }
;     }
;     __syncthreads();
.Lgb_have_flag:
	s_cmp_eq_u32 s40, 1
	s_cbranch_scc0 .Lgb_orig_g1
	s_and_b32 s40, s2, 7
	s_lshl_b32 s40, s40, 7
	s_add_u32 s38, s24, 0x313800
	s_addc_u32 s39, s25, 0
	v_mov_b32_e32 v0, s40
	v_mov_b32_e32 v1, 1
	global_atomic_add v0, v1, s[38:39]
	buffer_inv sc1
	v_mov_b32_e32 v4, 0x23fcc
	ds_read_b32 v2, v4
	s_mov_b32 s40, 0
	s_waitcnt lgkmcnt(0)
	v_add_u32_e32 v2, 32, v2
	ds_write_b32 v4, v2

; __device__ __forceinline__ unsigned xb_ld(unsigned* p)              { return __hip_atomic_load(p, __ATOMIC_RELAXED, __HIP_MEMORY_SCOPE_AGENT); }
; __device__ __forceinline__ unsigned xb_add(unsigned* p, unsigned v) { return __hip_atomic_fetch_add(p, v, __ATOMIC_RELAXED, __HIP_MEMORY_SCOPE_AGENT); }
; #define XB_SPIN(cond, bar) do { unsigned _sp = 0; while (cond) { __builtin_amdgcn_s_sleep(1); \
;     if ((++_sp & 255u) == 0u) { if (xb_ld(&(bar)[XB_TMO])) break; if (_sp > XB_SPIN_CAP) { atomicAdd(&(bar)[XB_TMO], 1u); break; } } } } while (0)
; __device__ __forceinline__ void xcd_barrier(const XcdBarrier& b) {
;     asm volatile("s_waitcnt vmcnt(0)" ::: "memory");
;     __syncthreads();
;     if (threadIdx.x == 0) {
;         unsigned* bar = b.bar;
;         __builtin_amdgcn_s_waitcnt(0);
;         unsigned nloc = b.st[0], nx = b.st[1];
;         if (nloc == 0u) { xcd_barrier_complete(bar, b.x, nloc, nx); b.st[0] = nloc; b.st[1] = nx; }
;         const unsigned old = xb_add(&bar[XB_XSUB(b.x)], 1u);
;         const unsigned gen = old / nloc;
;         if (old + 1u == (gen + 1u) * nloc) {
;             __builtin_amdgcn_fence(__ATOMIC_RELEASE, "agent");
;             asm volatile("s_waitcnt vmcnt(0)" ::: "memory");
;             const unsigned og = xb_add(&bar[XB_TOP], 1u);
;             const unsigned tg = og / nx;
;             if (og + 1u == (tg + 1u) * nx) xb_add(&bar[XB_TOPGEN], 1u);
;             else XB_SPIN(xb_ld(&bar[XB_TOPGEN]) == tg, bar);
;             __builtin_amdgcn_fence(__ATOMIC_ACQUIRE, "agent");
;             xb_add(&bar[XB_XGEN(b.x)], 1u);
;             asm volatile("s_waitcnt vmcnt(0)" ::: "memory");
;         } else {
;             XB_SPIN(xb_ld(&bar[XB_XGEN(b.x)]) == gen, bar);
;             __builtin_amdgcn_fence(__ATOMIC_ACQUIRE, "agent");
;             asm volatile("s_waitcnt vmcnt(0)" ::: "memory");
;         }
;     }
;     __syncthreads();
.LBB0_1245:
	s_add_i32 s0, s86, 1
	s_cmp_ge_i32 s0, s27
	s_cbranch_scc1 .LBB0_1299
	s_waitcnt vmcnt(0)
	s_waitcnt lgkmcnt(0)
	s_barrier
	s_mov_b64 s[0:1], exec
	v_readlane_b32 s8, v252, 32
	v_readlane_b32 s9, v252, 33
	v_readlane_b32 s44, v252, 46
	s_and_b64 s[8:9], s[0:1], s[8:9]
	v_readlane_b32 s45, v252, 47
	s_mov_b64 exec, s[8:9]
	s_cbranch_execz .LBB0_1298
	v_mov_b32_e32 v0, 0x23fc8
	ds_read_b32 v1, v0
	s_waitcnt lgkmcnt(0)
	v_readfirstlane_b32 s40, v1
	s_cmp_eq_u32 s40, 1
	s_cbranch_scc0 .Lgb_orig_pool
	s_and_b32 s40, s2, 7
	s_lshl_b32 s40, s40, 7
	s_add_u32 s38, s24, 0x313800
	s_addc_u32 s39, s25, 0
	v_mov_b32_e32 v0, s40
	v_mov_b32_e32 v1, 1
	global_atomic_add v0, v1, s[38:39]
	buffer_inv sc1
	v_mov_b32_e32 v4, 0x23fcc
	ds_read_b32 v2, v4
	s_mov_b32 s40, 0
	s_waitcnt lgkmcnt(0)
	v_add_u32_e32 v2, 32, v2
	ds_write_b32 v4, v2

; __device__ __forceinline__ unsigned xb_ld(unsigned* p)              { return __hip_atomic_load(p, __ATOMIC_RELAXED, __HIP_MEMORY_SCOPE_AGENT); }
; __device__ __forceinline__ unsigned xb_add(unsigned* p, unsigned v) { return __hip_atomic_fetch_add(p, v, __ATOMIC_RELAXED, __HIP_MEMORY_SCOPE_AGENT); }
; #define XB_SPIN(cond, bar) do { unsigned _sp = 0; while (cond) { __builtin_amdgcn_s_sleep(1); \
;     if ((++_sp & 255u) == 0u) { if (xb_ld(&(bar)[XB_TMO])) break; if (_sp > XB_SPIN_CAP) { atomicAdd(&(bar)[XB_TMO], 1u); break; } } } } while (0)
; __device__ __forceinline__ void xcd_barrier(const XcdBarrier& b) {
;     asm volatile("s_waitcnt vmcnt(0)" ::: "memory");
;     __syncthreads();
;     if (threadIdx.x == 0) {
;         unsigned* bar = b.bar;
;         __builtin_amdgcn_s_waitcnt(0);
;         unsigned nloc = b.st[0], nx = b.st[1];
;         if (nloc == 0u) { xcd_barrier_complete(bar, b.x, nloc, nx); b.st[0] = nloc; b.st[1] = nx; }
;         const unsigned old = xb_add(&bar[XB_XSUB(b.x)], 1u);
;         const unsigned gen = old / nloc;
;         if (old + 1u == (gen + 1u) * nloc) {
;             __builtin_amdgcn_fence(__ATOMIC_RELEASE, "agent");
;             asm volatile("s_waitcnt vmcnt(0)" ::: "memory");
;             const unsigned og = xb_add(&bar[XB_TOP], 1u);
;             const unsigned tg = og / nx;
;             if (og + 1u == (tg + 1u) * nx) xb_add(&bar[XB_TOPGEN], 1u);
;             else XB_SPIN(xb_ld(&bar[XB_TOPGEN]) == tg, bar);
;             __builtin_amdgcn_fence(__ATOMIC_ACQUIRE, "agent");
;             xb_add(&bar[XB_XGEN(b.x)], 1u);
;             asm volatile("s_waitcnt vmcnt(0)" ::: "memory");
;         } else {
;             XB_SPIN(xb_ld(&bar[XB_XGEN(b.x)]) == gen, bar);
;             __builtin_amdgcn_fence(__ATOMIC_ACQUIRE, "agent");
;             asm volatile("s_waitcnt vmcnt(0)" ::: "memory");
;         }
;     }
;     __syncthreads();
.LBB0_1377:
	s_add_i32 s66, s86, 2
	s_cmp_ge_i32 s66, s27
	s_cbranch_scc1 .LBB0_1389
	s_waitcnt vmcnt(0)
	s_waitcnt lgkmcnt(0)
	s_barrier
	s_mov_b64 s[0:1], exec
	v_readlane_b32 s38, v252, 32
	v_readlane_b32 s39, v252, 33
	v_readlane_b32 s46, v252, 46
	s_and_b64 s[38:39], s[0:1], s[38:39]
	v_readlane_b32 s47, v252, 47
	s_mov_b64 exec, s[38:39]
	s_cbranch_execz .LBB0_1617
	v_mov_b32_e32 v0, 0x23fc8
	ds_read_b32 v1, v0
	s_waitcnt lgkmcnt(0)
	v_readfirstlane_b32 s40, v1
	s_cmp_eq_u32 s40, 1
	s_cbranch_scc0 .Lgb_orig_attn
	s_and_b32 s40, s2, 7
	s_lshl_b32 s40, s40, 7
	s_add_u32 s38, s24, 0x313800
	s_addc_u32 s39, s25, 0
	v_mov_b32_e32 v0, s40
	v_mov_b32_e32 v1, 1
	global_atomic_add v0, v1, s[38:39]
	buffer_inv sc1
	v_mov_b32_e32 v4, 0x23fcc
	ds_read_b32 v2, v4
	s_mov_b32 s40, 0
	s_waitcnt lgkmcnt(0)
	v_add_u32_e32 v2, 32, v2
	ds_write_b32 v4, v2

; __device__ __forceinline__ unsigned xb_ld(unsigned* p)              { return __hip_atomic_load(p, __ATOMIC_RELAXED, __HIP_MEMORY_SCOPE_AGENT); }
; __device__ __forceinline__ unsigned xb_add(unsigned* p, unsigned v) { return __hip_atomic_fetch_add(p, v, __ATOMIC_RELAXED, __HIP_MEMORY_SCOPE_AGENT); }
; #define XB_SPIN(cond, bar) do { unsigned _sp = 0; while (cond) { __builtin_amdgcn_s_sleep(1); \
;     if ((++_sp & 255u) == 0u) { if (xb_ld(&(bar)[XB_TMO])) break; if (_sp > XB_SPIN_CAP) { atomicAdd(&(bar)[XB_TMO], 1u); break; } } } } while (0)
; __device__ __forceinline__ void xcd_barrier(const XcdBarrier& b) {
;     asm volatile("s_waitcnt vmcnt(0)" ::: "memory");
;     __syncthreads();
;     if (threadIdx.x == 0) {
;         unsigned* bar = b.bar;
;         __builtin_amdgcn_s_waitcnt(0);
;         unsigned nloc = b.st[0], nx = b.st[1];
;         if (nloc == 0u) { xcd_barrier_complete(bar, b.x, nloc, nx); b.st[0] = nloc; b.st[1] = nx; }
;         const unsigned old = xb_add(&bar[XB_XSUB(b.x)], 1u);
;         const unsigned gen = old / nloc;
;         if (old + 1u == (gen + 1u) * nloc) {
;             __builtin_amdgcn_fence(__ATOMIC_RELEASE, "agent");
;             asm volatile("s_waitcnt vmcnt(0)" ::: "memory");
;             const unsigned og = xb_add(&bar[XB_TOP], 1u);
;             const unsigned tg = og / nx;
;             if (og + 1u == (tg + 1u) * nx) xb_add(&bar[XB_TOPGEN], 1u);
;             else XB_SPIN(xb_ld(&bar[XB_TOPGEN]) == tg, bar);
;             __builtin_amdgcn_fence(__ATOMIC_ACQUIRE, "agent");
;             xb_add(&bar[XB_XGEN(b.x)], 1u);
;             asm volatile("s_waitcnt vmcnt(0)" ::: "memory");
;         } else {
;             XB_SPIN(xb_ld(&bar[XB_XGEN(b.x)]) == gen, bar);
;             __builtin_amdgcn_fence(__ATOMIC_ACQUIRE, "agent");
;             asm volatile("s_waitcnt vmcnt(0)" ::: "memory");
;         }
;     }
;     __syncthreads();
.LBB0_1672:
	s_add_i32 s8, s66, 1
	s_cmp_ge_i32 s8, s27
	s_cbranch_scc1 .LBB0_1684
	s_waitcnt vmcnt(0)
	s_waitcnt lgkmcnt(0)
	s_barrier
	s_mov_b64 s[0:1], exec
	v_readlane_b32 s38, v252, 32
	v_readlane_b32 s39, v252, 33
	v_readlane_b32 s46, v252, 46
	s_and_b64 s[38:39], s[0:1], s[38:39]
	v_readlane_b32 s47, v252, 47
	s_mov_b64 exec, s[38:39]
	s_cbranch_execz .LBB0_1727
	v_mov_b32_e32 v0, 0x23fc8
	ds_read_b32 v1, v0
	s_waitcnt lgkmcnt(0)
	v_readfirstlane_b32 s40, v1
	s_cmp_eq_u32 s40, 1
	s_cbranch_scc0 .Lgb_orig_g2
	s_and_b32 s40, s2, 7
	s_lshl_b32 s40, s40, 7
	s_add_u32 s38, s24, 0x313800
	s_addc_u32 s39, s25, 0
	v_mov_b32_e32 v0, s40
	v_mov_b32_e32 v1, 1
	global_atomic_add v0, v1, s[38:39]
	buffer_inv sc1
	v_mov_b32_e32 v4, 0x23fcc
	ds_read_b32 v2, v4
	s_mov_b32 s40, 0
	s_waitcnt lgkmcnt(0)
	v_add_u32_e32 v2, 32, v2
	ds_write_b32 v4, v2

; __device__ __forceinline__ unsigned xb_ld(unsigned* p)              { return __hip_atomic_load(p, __ATOMIC_RELAXED, __HIP_MEMORY_SCOPE_AGENT); }
; __device__ __forceinline__ unsigned xb_add(unsigned* p, unsigned v) { return __hip_atomic_fetch_add(p, v, __ATOMIC_RELAXED, __HIP_MEMORY_SCOPE_AGENT); }
; #define XB_SPIN(cond, bar) do { unsigned _sp = 0; while (cond) { __builtin_amdgcn_s_sleep(1); \
;     if ((++_sp & 255u) == 0u) { if (xb_ld(&(bar)[XB_TMO])) break; if (_sp > XB_SPIN_CAP) { atomicAdd(&(bar)[XB_TMO], 1u); break; } } } } while (0)
; __device__ __forceinline__ void xcd_barrier(const XcdBarrier& b) {
;     asm volatile("s_waitcnt vmcnt(0)" ::: "memory");
;     __syncthreads();
;     if (threadIdx.x == 0) {
;         unsigned* bar = b.bar;
;         __builtin_amdgcn_s_waitcnt(0);
;         unsigned nloc = b.st[0], nx = b.st[1];
;         if (nloc == 0u) { xcd_barrier_complete(bar, b.x, nloc, nx); b.st[0] = nloc; b.st[1] = nx; }
;         const unsigned old = xb_add(&bar[XB_XSUB(b.x)], 1u);
;         const unsigned gen = old / nloc;
;         if (old + 1u == (gen + 1u) * nloc) {
;             __builtin_amdgcn_fence(__ATOMIC_RELEASE, "agent");
;             asm volatile("s_waitcnt vmcnt(0)" ::: "memory");
;             const unsigned og = xb_add(&bar[XB_TOP], 1u);
;             const unsigned tg = og / nx;
;             if (og + 1u == (tg + 1u) * nx) xb_add(&bar[XB_TOPGEN], 1u);
;             else XB_SPIN(xb_ld(&bar[XB_TOPGEN]) == tg, bar);
;             __builtin_amdgcn_fence(__ATOMIC_ACQUIRE, "agent");
;             xb_add(&bar[XB_XGEN(b.x)], 1u);
;             asm volatile("s_waitcnt vmcnt(0)" ::: "memory");
;         } else {
;             XB_SPIN(xb_ld(&bar[XB_XGEN(b.x)]) == gen, bar);
;             __builtin_amdgcn_fence(__ATOMIC_ACQUIRE, "agent");
;             asm volatile("s_waitcnt vmcnt(0)" ::: "memory");
;         }
;     }
;     __syncthreads();
.LBB0_1775:
	s_add_i32 s8, s66, 2
	s_cmp_ge_i32 s8, s27
	s_cbranch_scc1 .LBB0_1829
	s_waitcnt vmcnt(0)
	s_waitcnt vmcnt(0) lgkmcnt(0)
	s_barrier
	s_mov_b64 s[0:1], exec
	v_readlane_b32 s38, v252, 32
	v_readlane_b32 s39, v252, 33
	s_and_b64 s[38:39], s[0:1], s[38:39]
	s_mov_b64 exec, s[38:39]
	s_cbranch_execz .LBB0_1828
	v_mov_b32_e32 v0, 0x23fc8
	ds_read_b32 v1, v0
	s_waitcnt lgkmcnt(0)
	v_readfirstlane_b32 s40, v1
	s_cmp_eq_u32 s40, 1
	s_cbranch_scc0 .Lgb_orig_g3
	s_and_b32 s40, s2, 7
	s_lshl_b32 s40, s40, 7
	s_add_u32 s38, s24, 0x313800
	s_addc_u32 s39, s25, 0
	v_mov_b32_e32 v0, s40
	v_mov_b32_e32 v1, 1
	global_atomic_add v0, v1, s[38:39]
	buffer_inv sc1
	v_mov_b32_e32 v4, 0x23fcc
	ds_read_b32 v2, v4
	s_mov_b32 s40, 0
	s_waitcnt lgkmcnt(0)
	v_add_u32_e32 v2, 32, v2
	ds_write_b32 v4, v2

; __device__ __forceinline__ unsigned xb_ld(unsigned* p)              { return __hip_atomic_load(p, __ATOMIC_RELAXED, __HIP_MEMORY_SCOPE_AGENT); }
; __device__ __forceinline__ unsigned xb_add(unsigned* p, unsigned v) { return __hip_atomic_fetch_add(p, v, __ATOMIC_RELAXED, __HIP_MEMORY_SCOPE_AGENT); }
; #define XB_SPIN(cond, bar) do { unsigned _sp = 0; while (cond) { __builtin_amdgcn_s_sleep(1); \
;     if ((++_sp & 255u) == 0u) { if (xb_ld(&(bar)[XB_TMO])) break; if (_sp > XB_SPIN_CAP) { atomicAdd(&(bar)[XB_TMO], 1u); break; } } } } while (0)
; __device__ __forceinline__ void xcd_barrier(const XcdBarrier& b) {
;     asm volatile("s_waitcnt vmcnt(0)" ::: "memory");
;     __syncthreads();
;     if (threadIdx.x == 0) {
;         unsigned* bar = b.bar;
;         __builtin_amdgcn_s_waitcnt(0);
;         unsigned nloc = b.st[0], nx = b.st[1];
;         if (nloc == 0u) { xcd_barrier_complete(bar, b.x, nloc, nx); b.st[0] = nloc; b.st[1] = nx; }
;         const unsigned old = xb_add(&bar[XB_XSUB(b.x)], 1u);
;         const unsigned gen = old / nloc;
;         if (old + 1u == (gen + 1u) * nloc) {
;             __builtin_amdgcn_fence(__ATOMIC_RELEASE, "agent");
;             asm volatile("s_waitcnt vmcnt(0)" ::: "memory");
;             const unsigned og = xb_add(&bar[XB_TOP], 1u);
;             const unsigned tg = og / nx;
;             if (og + 1u == (tg + 1u) * nx) xb_add(&bar[XB_TOPGEN], 1u);
;             else XB_SPIN(xb_ld(&bar[XB_TOPGEN]) == tg, bar);
;             __builtin_amdgcn_fence(__ATOMIC_ACQUIRE, "agent");
;             xb_add(&bar[XB_XGEN(b.x)], 1u);
;             asm volatile("s_waitcnt vmcnt(0)" ::: "memory");
;         } else {
;             XB_SPIN(xb_ld(&bar[XB_XGEN(b.x)]) == gen, bar);
;             __builtin_amdgcn_fence(__ATOMIC_ACQUIRE, "agent");
;             asm volatile("s_waitcnt vmcnt(0)" ::: "memory");
;         }
;     }
;     __syncthreads();
.LBB0_1868:
	s_add_i32 s0, s66, 3
	s_mov_b32 s86, s0
	s_cmp_ge_i32 s0, s27
	s_cbranch_scc1 .LBB0_1922
	s_waitcnt vmcnt(0)
	s_waitcnt vmcnt(0) lgkmcnt(0)
	s_barrier
	s_mov_b64 s[0:1], exec
	v_readlane_b32 s8, v252, 32
	v_readlane_b32 s9, v252, 33
	s_and_b64 s[8:9], s[0:1], s[8:9]
	s_mov_b64 exec, s[8:9]
	s_cbranch_execz .LBB0_1921
	s_cmp_eq_u32 s86, 20
	s_cbranch_scc1 .Lgb_orig_g4
	v_mov_b32_e32 v0, 0x23fc8
	ds_read_b32 v1, v0
	s_waitcnt lgkmcnt(0)
	v_readfirstlane_b32 s40, v1
	s_cmp_eq_u32 s40, 1
	s_cbranch_scc0 .Lgb_orig_g4
	s_and_b32 s40, s2, 7
	s_lshl_b32 s40, s40, 7
	s_add_u32 s38, s24, 0x313800
	s_addc_u32 s39, s25, 0
	v_mov_b32_e32 v0, s40
	v_mov_b32_e32 v1, 1
	global_atomic_add v0, v1, s[38:39]
	buffer_inv sc1
	v_mov_b32_e32 v4, 0x23fcc
	ds_read_b32 v2, v4
	s_mov_b32 s40, 0
	s_waitcnt lgkmcnt(0)
	v_add_u32_e32 v2, 32, v2
	ds_write_b32 v4, v2
